# P7: the eight per-row rstd loads of the up-projection epilogue issued before the tile's K loop (registers v226-233)
# baseline (speedup 1.0000x reference)
.LBB0_1416:
	v_lshl_add_u32 v234, s60, 8, v1
	v_ashrrev_i32_e32 v235, 31, v234
	v_lshl_add_u64 v[234:235], v[234:235], 2, s[22:23]
	global_load_dword v226, v[234:235], off
	global_load_dword v227, v[234:235], off offset:64
	global_load_dword v228, v[234:235], off offset:128
	global_load_dword v229, v[234:235], off offset:192
	global_load_dword v230, v[234:235], off offset:512
	global_load_dword v231, v[234:235], off offset:576
	global_load_dword v232, v[234:235], off offset:640
	global_load_dword v233, v[234:235], off offset:704
	s_ashr_i32 s27, s26, 31
	s_lshl_b64 s[44:45], s[26:27], 19
	s_add_u32 s56, s2, s44
	s_addc_u32 s57, s3, s45
	s_ashr_i32 s55, s54, 31
	s_lshl_b64 s[44:45], s[54:55], 19
	s_add_u32 s58, s4, s44
	s_addc_u32 s59, s5, s45
	s_cmp_eq_u32 s42, 0
	s_cbranch_scc1 .LBB0_1448
	s_and_b64 s[44:45], s[12:13], exec
	s_cselect_b32 s27, s57, s65
	s_cselect_b32 s43, s56, s64
	s_cselect_b32 s44, s59, s71
	s_cselect_b32 s45, s58, s70
	s_add_i32 s48, s42, -2
	s_add_u32 s64, s64, 0x40080
	s_addc_u32 s65, s65, 0
	s_add_u32 s49, s70, 0x100
	v_mov_b32_e32 v2, 0
	s_addc_u32 s50, s71, 0
	s_mov_b32 s51, 0
	v_mov_b32_e32 v3, v2
	v_mov_b32_e32 v4, v2
	v_mov_b32_e32 v5, v2
	v_mov_b32_e32 v6, v2
	v_mov_b32_e32 v7, v2
	v_mov_b32_e32 v8, v2
	v_mov_b32_e32 v9, v2
	v_mov_b32_e32 v10, v2
	v_mov_b32_e32 v11, v2
	v_mov_b32_e32 v12, v2
	v_mov_b32_e32 v13, v2
	v_mov_b32_e32 v14, v2
	v_mov_b32_e32 v15, v2
	v_mov_b32_e32 v16, v2
	v_mov_b32_e32 v17, v2
	v_mov_b32_e32 v18, v2
	v_mov_b32_e32 v19, v2
	v_mov_b32_e32 v20, v2
	v_mov_b32_e32 v21, v2
	v_mov_b32_e32 v22, v2
	v_mov_b32_e32 v23, v2
	v_mov_b32_e32 v24, v2
	v_mov_b32_e32 v25, v2
	v_mov_b32_e32 v26, v2
	v_mov_b32_e32 v27, v2
	v_mov_b32_e32 v28, v2
	v_mov_b32_e32 v29, v2
	v_mov_b32_e32 v30, v2
	v_mov_b32_e32 v31, v2
	v_mov_b32_e32 v32, v2
	v_mov_b32_e32 v33, v2
	v_mov_b32_e32 v66, v2
	v_mov_b32_e32 v67, v2
	v_mov_b32_e32 v68, v2
	v_mov_b32_e32 v69, v2
	v_mov_b32_e32 v70, v2
	v_mov_b32_e32 v71, v2
	v_mov_b32_e32 v72, v2
	v_mov_b32_e32 v73, v2
	v_mov_b32_e32 v74, v2
	v_mov_b32_e32 v75, v2
	v_mov_b32_e32 v76, v2
	v_mov_b32_e32 v77, v2
	v_mov_b32_e32 v78, v2
	v_mov_b32_e32 v79, v2
	v_mov_b32_e32 v80, v2
	v_mov_b32_e32 v81, v2
	v_mov_b32_e32 v82, v2
	v_mov_b32_e32 v83, v2
	v_mov_b32_e32 v84, v2
	v_mov_b32_e32 v85, v2
	v_mov_b32_e32 v86, v2
	v_mov_b32_e32 v87, v2
	v_mov_b32_e32 v88, v2
	v_mov_b32_e32 v89, v2
	v_mov_b32_e32 v90, v2
	v_mov_b32_e32 v91, v2
	v_mov_b32_e32 v92, v2
	v_mov_b32_e32 v93, v2
	v_mov_b32_e32 v94, v2
	v_mov_b32_e32 v95, v2
	v_mov_b32_e32 v96, v2
	v_mov_b32_e32 v97, v2
	v_mov_b32_e32 v34, v2
	v_mov_b32_e32 v35, v2
	v_mov_b32_e32 v36, v2
	v_mov_b32_e32 v37, v2
	v_mov_b32_e32 v38, v2
	v_mov_b32_e32 v39, v2
	v_mov_b32_e32 v40, v2
	v_mov_b32_e32 v41, v2
	v_mov_b32_e32 v42, v2
	v_mov_b32_e32 v43, v2
	v_mov_b32_e32 v44, v2
	v_mov_b32_e32 v45, v2
	v_mov_b32_e32 v46, v2
	v_mov_b32_e32 v47, v2
	v_mov_b32_e32 v48, v2
	v_mov_b32_e32 v49, v2
	v_mov_b32_e32 v50, v2
	v_mov_b32_e32 v51, v2
	v_mov_b32_e32 v52, v2
	v_mov_b32_e32 v53, v2
	v_mov_b32_e32 v54, v2
	v_mov_b32_e32 v55, v2
	v_mov_b32_e32 v56, v2
	v_mov_b32_e32 v57, v2
	v_mov_b32_e32 v58, v2
	v_mov_b32_e32 v59, v2
	v_mov_b32_e32 v60, v2
	v_mov_b32_e32 v61, v2
	v_mov_b32_e32 v62, v2
	v_mov_b32_e32 v63, v2
	v_mov_b32_e32 v64, v2
	v_mov_b32_e32 v65, v2
	v_mov_b32_e32 v98, v2
	v_mov_b32_e32 v99, v2
	v_mov_b32_e32 v100, v2
	v_mov_b32_e32 v101, v2
	v_mov_b32_e32 v102, v2
	v_mov_b32_e32 v103, v2
	v_mov_b32_e32 v104, v2
	v_mov_b32_e32 v105, v2
	v_mov_b32_e32 v106, v2
	v_mov_b32_e32 v107, v2
	v_mov_b32_e32 v108, v2
	v_mov_b32_e32 v109, v2
	v_mov_b32_e32 v110, v2
	v_mov_b32_e32 v111, v2
	v_mov_b32_e32 v112, v2
	v_mov_b32_e32 v113, v2
	v_mov_b32_e32 v114, v2
	v_mov_b32_e32 v115, v2
	v_mov_b32_e32 v116, v2
	v_mov_b32_e32 v117, v2
	v_mov_b32_e32 v118, v2
	v_mov_b32_e32 v119, v2
	v_mov_b32_e32 v120, v2
	v_mov_b32_e32 v121, v2
	v_mov_b32_e32 v154, v2
	v_mov_b32_e32 v155, v2
	v_mov_b32_e32 v156, v2
	v_mov_b32_e32 v157, v2
	v_mov_b32_e32 v158, v2
	v_mov_b32_e32 v159, v2
	v_mov_b32_e32 v160, v2
	v_mov_b32_e32 v161, v2

.LBB0_1421:
	v_lshl_add_u32 v122, s60, 8, v1
	v_ashrrev_i32_e32 v123, 31, v122
	s_lshl_b32 s27, s62, 8
	v_lshl_add_u64 v[124:125], v[122:123], 2, s[22:23]
	v_add_u32_e32 v126, 0x80, v122
	v_add_u32_e32 v128, 0x90, v122
	v_add_u32_e32 v130, 0xa0, v122
	v_add_u32_e32 v122, 0xb0, v122
	s_or_b32 s27, s27, s75
	v_ashrrev_i32_e32 v127, 31, v126
	v_ashrrev_i32_e32 v129, 31, v128
	v_ashrrev_i32_e32 v131, 31, v130
	v_ashrrev_i32_e32 v123, 31, v122
	s_ashr_i32 s27, s27, 1
	v_lshl_add_u64 v[126:127], v[126:127], 2, s[22:23]
	v_lshl_add_u64 v[128:129], v[128:129], 2, s[22:23]
	v_lshl_add_u64 v[130:131], v[130:131], 2, s[22:23]
	v_lshl_add_u64 v[122:123], v[122:123], 2, s[22:23]
	v_or_b32_e32 v184, s27, v217
	v_ashrrev_i32_e32 v185, 31, v184
	v_readlane_b32 s36, v245, 19
	v_lshlrev_b64 v[134:135], 2, v[184:185]
	v_readlane_b32 s42, v245, 25
	v_readlane_b32 s43, v245, 26
	v_readlane_b32 s44, v245, 27
	v_readlane_b32 s45, v245, 28
	v_lshl_add_u64 v[196:197], s[42:43], 0, v[134:135]
	v_lshl_add_u64 v[122:123], s[30:31], 0, v[134:135]
	v_lshl_add_u64 v[124:125], s[88:89], 0, v[134:135]
	global_load_dwordx4 v[146:149], v[196:197], off
	global_load_dwordx4 v[142:145], v[122:123], off
	global_load_dwordx4 v[138:141], v[124:125], off
	v_lshl_add_u64 v[198:199], s[44:45], 0, v[134:135]
	v_lshl_add_u64 v[122:123], s[90:91], 0, v[134:135]
	v_lshl_add_u64 v[124:125], s[92:93], 0, v[134:135]
	v_lshl_add_u64 v[126:127], s[94:95], 0, v[134:135]
	v_lshl_add_u64 v[134:135], s[52:53], 0, v[134:135]
	global_load_dwordx4 v[150:153], v[198:199], off
	global_load_dwordx4 v[130:133], v[122:123], off
	s_nop 0
	global_load_dwordx4 v[122:125], v[124:125], off
	s_lshl_b32 s27, s60, 2
	global_load_dwordx4 v[126:129], v[126:127], off
	global_load_dwordx4 v[134:137], v[134:135], off
	s_add_i32 s60, s27, s33
	v_lshl_or_b32 v179, s60, 6, v166
	v_readlane_b32 s37, v245, 20
	v_readlane_b32 s38, v245, 21
	v_readlane_b32 s39, v245, 22
	v_readlane_b32 s40, v245, 23
	v_readlane_b32 s41, v245, 24
	v_readlane_b32 s46, v245, 29
	v_readlane_b32 s47, v245, 30
	v_readlane_b32 s48, v245, 31
	v_readlane_b32 s49, v245, 32
	v_readlane_b32 s50, v245, 33
	v_readlane_b32 s51, v245, 34
	s_waitcnt vmcnt(0)
	v_mov_b32_e32 v194, v226
	v_mov_b32_e32 v192, v227
	v_mov_b32_e32 v190, v228
	v_mov_b32_e32 v188, v229
	v_mov_b32_e32 v186, v230
	v_mov_b32_e32 v182, v231
	v_mov_b32_e32 v180, v232
	v_mov_b32_e32 v178, v233
	v_pk_mul_f32 v[160:161], v[160:161], v[194:195] op_sel_hi:[1,0]
	v_pk_mul_f32 v[158:159], v[158:159], v[194:195] op_sel_hi:[1,0]
	v_pk_mul_f32 v[156:157], v[156:157], v[194:195] op_sel_hi:[1,0]
	v_pk_mul_f32 v[154:155], v[154:155], v[194:195] op_sel_hi:[1,0]
	v_mov_b32_dpp v204, v158 row_ror:1 row_mask:0xf bank_mask:0xf
	v_mov_b32_dpp v205, v159 row_ror:1 row_mask:0xf bank_mask:0xf
	v_mov_b32_dpp v206, v160 row_ror:1 row_mask:0xf bank_mask:0xf
	v_mov_b32_dpp v207, v161 row_ror:1 row_mask:0xf bank_mask:0xf
	v_mov_b32_dpp v208, v158 row_ror:2 row_mask:0xf bank_mask:0xf
	v_mov_b32_dpp v209, v159 row_ror:2 row_mask:0xf bank_mask:0xf
	v_mov_b32_dpp v210, v160 row_ror:2 row_mask:0xf bank_mask:0xf
	v_mov_b32_dpp v211, v161 row_ror:2 row_mask:0xf bank_mask:0xf
	v_mov_b32_dpp v200, v154 row_ror:1 row_mask:0xf bank_mask:0xf
	v_mov_b32_dpp v201, v155 row_ror:1 row_mask:0xf bank_mask:0xf
	v_mov_b32_dpp v202, v156 row_ror:1 row_mask:0xf bank_mask:0xf
	v_mov_b32_dpp v203, v157 row_ror:1 row_mask:0xf bank_mask:0xf
	v_mov_b32_dpp v212, v154 row_ror:2 row_mask:0xf bank_mask:0xf
	v_mov_b32_dpp v213, v155 row_ror:2 row_mask:0xf bank_mask:0xf
	v_mov_b32_dpp v214, v156 row_ror:2 row_mask:0xf bank_mask:0xf
	v_mov_b32_dpp v215, v157 row_ror:2 row_mask:0xf bank_mask:0xf
	v_mov_b32_dpp v204, v158 row_shr:1 row_mask:0xf bank_mask:0xf
	v_mov_b32_dpp v205, v159 row_shr:1 row_mask:0xf bank_mask:0xf
	v_mov_b32_dpp v206, v160 row_shr:1 row_mask:0xf bank_mask:0xf
	v_mov_b32_dpp v207, v161 row_shr:1 row_mask:0xf bank_mask:0xf
	v_mov_b32_dpp v208, v158 row_shr:2 row_mask:0xf bank_mask:0xf
	v_mov_b32_dpp v209, v159 row_shr:2 row_mask:0xf bank_mask:0xf
	v_mov_b32_dpp v210, v160 row_shr:2 row_mask:0xf bank_mask:0xf
	v_mov_b32_dpp v211, v161 row_shr:2 row_mask:0xf bank_mask:0xf
	v_mov_b32_dpp v200, v154 row_shr:1 row_mask:0xf bank_mask:0xf
	v_mov_b32_dpp v201, v155 row_shr:1 row_mask:0xf bank_mask:0xf
	v_mov_b32_dpp v202, v156 row_shr:1 row_mask:0xf bank_mask:0xf
	v_mov_b32_dpp v203, v157 row_shr:1 row_mask:0xf bank_mask:0xf
	v_mov_b32_dpp v212, v154 row_shr:2 row_mask:0xf bank_mask:0xf
	v_mov_b32_dpp v213, v155 row_shr:2 row_mask:0xf bank_mask:0xf
	v_mov_b32_dpp v214, v156 row_shr:2 row_mask:0xf bank_mask:0xf
	v_mov_b32_dpp v215, v157 row_shr:2 row_mask:0xf bank_mask:0xf
	s_and_saveexec_b64 s[62:63], s[6:7]
	s_cbranch_execz .LBB0_1423
	v_pk_fma_f32 v[210:211], v[148:149], v[210:211], v[152:153]
	v_pk_fma_f32 v[208:209], v[146:147], v[208:209], v[150:151]
	v_pk_fma_f32 v[206:207], v[144:145], v[206:207], v[210:211]
	v_pk_fma_f32 v[204:205], v[142:143], v[204:205], v[208:209]
	v_pk_fma_f32 v[206:207], v[160:161], v[140:141], v[206:207]
	v_pk_fma_f32 v[204:205], v[158:159], v[138:139], v[204:205]
	v_mul_f32_e32 v181, 0xbfb8aa3b, v207
	v_exp_f32_e32 v181, v181
	v_mul_f32_e32 v183, 0xbfb8aa3b, v206
	v_exp_f32_e32 v183, v183
	v_mul_f32_e32 v187, 0xbfb8aa3b, v204
	v_add_f32_e32 v181, 1.0, v181
	v_rcp_f32_e32 v209, v181
	v_add_f32_e32 v181, 1.0, v183
	v_mul_f32_e32 v183, 0xbfb8aa3b, v205
	v_exp_f32_e32 v183, v183
	v_exp_f32_e32 v187, v187
	v_rcp_f32_e32 v208, v181
	v_pk_fma_f32 v[212:213], v[130:131], v[212:213], v[134:135]
	v_add_f32_e32 v181, 1.0, v183
	v_rcp_f32_e32 v211, v181
	v_add_f32_e32 v181, 1.0, v187
	v_rcp_f32_e32 v210, v181
	v_pk_fma_f32 v[214:215], v[132:133], v[214:215], v[136:137]
	v_pk_fma_f32 v[200:201], v[122:123], v[200:201], v[212:213]
	v_pk_fma_f32 v[202:203], v[124:125], v[202:203], v[214:215]
	v_pk_fma_f32 v[200:201], v[154:155], v[126:127], v[200:201]
	v_pk_mul_f32 v[204:205], v[204:205], v[210:211]
	v_pk_fma_f32 v[202:203], v[156:157], v[128:129], v[202:203]
	v_pk_mul_f32 v[200:201], v[204:205], v[200:201]
	v_pk_mul_f32 v[204:205], v[206:207], v[208:209]
	v_cvt_pk_bf16_f32 v200, v200, v201
	v_pk_mul_f32 v[202:203], v[204:205], v[202:203]
	v_mov_b64_e32 v[204:205], s[18:19]
	v_mad_i64_i32 v[204:205], s[42:43], v179, s82, v[204:205]
	v_lshl_add_u64 v[204:205], v[184:185], 1, v[204:205]
	v_cvt_pk_bf16_f32 v201, v202, v203
	global_store_dwordx2 v[204:205], v[200:201], off
